# FFN-out epilogues: second-half LN vector loads hoisted to the epilogue start, vmcnt(0) fences replaced by counted waits at the z loads first consumers; on top of v11
# baseline (speedup 1.0000x reference)
.LBB0_610:
	s_lshl_b32 s1, s57, 8
	v_mbcnt_lo_u32_b32 v198, -1, 0
	v_mbcnt_hi_u32_b32 v198, -1, v198
	s_lshl_b32 s0, s51, 18
	v_and_or_b32 v208, v198, 15, s56
	v_ashrrev_i32_e32 v112, 1, v198
	s_or_b32 s1, s1, s58
	v_lshlrev_b32_e32 v2, 10, v208
	v_and_b32_e32 v112, -8, v112
	s_add_i32 s0, s1, s0
	v_add3_u32 v2, s0, v112, v2
	v_add_u32_e32 v174, s1, v112
	v_lshl_add_u64 v[148:149], v[2:3], 1, s[10:11]
	v_ashrrev_i32_e32 v175, 31, v174
	global_load_dwordx4 v[176:179], v[148:149], off
	v_lshlrev_b64 v[112:113], 2, v[174:175]
	v_lshl_add_u64 v[170:171], s[16:17], 0, v[112:113]
	v_lshl_add_u64 v[172:173], s[18:19], 0, v[112:113]
	global_load_dwordx4 v[180:183], v[170:171], off
	global_load_dwordx4 v[184:187], v[172:173], off
	global_load_dwordx4 v[188:191], v[170:171], off offset:16
	global_load_dwordx4 v[194:197], v[172:173], off offset:16
	global_load_dwordx4 v[216:219], v[172:173], off offset:528
	global_load_dwordx4 v[220:223], v[172:173], off offset:512
	global_load_dwordx4 v[224:227], v[170:171], off offset:528
	global_load_dwordx4 v[228:231], v[170:171], off offset:512
	v_add_co_u32_e32 v150, vcc, 0x8000, v148
	v_mov_b32_e32 v113, v3
	v_mov_b32_e32 v115, v3
	v_mov_b32_e32 v121, v3
	v_add_u32_e32 v112, 0x20000, v2
	v_add_u32_e32 v114, 0x24000, v2
	v_add_u32_e32 v120, 0x28000, v2
	v_addc_co_u32_e32 v151, vcc, 0, v149, vcc
	s_mov_b32 s79, 0x10000
	v_mov_b32_e32 v123, v3
	v_add_u32_e32 v122, 0x2c000, v2
	v_lshl_add_u64 v[112:113], v[112:113], 1, s[10:11]
	v_lshl_add_u64 v[114:115], v[114:115], 1, s[10:11]
	v_lshl_add_u64 v[120:121], v[120:121], 1, s[10:11]
	v_add_co_u32_e32 v154, vcc, s79, v148
	v_lshl_add_u64 v[152:153], v[122:123], 1, s[10:11]
	global_load_dwordx4 v[144:147], v[112:113], off
	global_load_dwordx4 v[132:135], v[114:115], off
	s_nop 0
	global_load_dwordx4 v[120:123], v[120:121], off
	s_nop 0
	global_load_dwordx4 v[112:115], v[152:153], off
	global_load_dwordx4 v[156:159], v[150:151], off
	v_addc_co_u32_e32 v155, vcc, 0, v149, vcc
	v_add_co_u32_e32 v148, vcc, s92, v148
	s_lshl_b32 s0, s60, 11
	s_nop 0
	v_addc_co_u32_e32 v149, vcc, 0, v149, vcc
	global_load_dwordx4 v[152:155], v[154:155], off
	s_nop 0
	global_load_dwordx4 v[148:151], v[148:149], off
	s_add_i32 s0, s0, 0
	v_lshl_add_u32 v175, v208, 3, s0
	v_add_u32_e32 v175, 0x20200, v175
	ds_read_b64 v[192:193], v175
	v_cmp_gt_u32_e32 vcc, 16, v198
	s_lshl_b32 s0, s51, 8
	v_add_u32_e32 v207, s0, v208
	v_lshlrev_b32_e32 v206, 10, v207
	s_waitcnt lgkmcnt(0)
	v_mul_f32_e64 v198, v193, -v192
	s_waitcnt vmcnt(0)
	v_lshlrev_b32_e32 v200, 16, v176
	v_and_b32_e32 v201, 0xffff0000, v176
	v_lshlrev_b32_e32 v176, 16, v177
	v_and_b32_e32 v177, 0xffff0000, v177
	v_lshlrev_b32_e32 v202, 16, v178
	v_and_b32_e32 v203, 0xffff0000, v178
	v_lshlrev_b32_e32 v178, 16, v179
	v_and_b32_e32 v179, 0xffff0000, v179
	v_pk_fma_f32 v[210:211], v[192:193], v[200:201], v[198:199] op_sel:[1,0,0] op_sel_hi:[1,1,0]
	v_pk_fma_f32 v[212:213], v[192:193], v[176:177], v[198:199] op_sel:[1,0,0] op_sel_hi:[1,1,0]
	v_pk_fma_f32 v[214:215], v[192:193], v[202:203], v[198:199] op_sel:[1,0,0] op_sel_hi:[1,1,0]
	v_pk_fma_f32 v[192:193], v[192:193], v[178:179], v[198:199] op_sel:[1,0,0] op_sel_hi:[1,1,0]
	v_pk_mul_f32 v[176:177], v[180:181], s[94:95] op_sel_hi:[1,0]
	v_pk_mul_f32 v[178:179], v[184:185], s[94:95] op_sel_hi:[1,0]
	v_pk_mul_f32 v[180:181], v[182:183], s[94:95] op_sel_hi:[1,0]
	v_pk_mul_f32 v[182:183], v[186:187], s[94:95] op_sel_hi:[1,0]
	v_pk_mul_f32 v[184:185], v[188:189], s[94:95] op_sel_hi:[1,0]
	v_pk_mul_f32 v[200:201], v[190:191], s[94:95] op_sel_hi:[1,0]
	v_pk_mul_f32 v[202:203], v[196:197], s[94:95] op_sel_hi:[1,0]
	v_pk_fma_f32 v[188:189], v[176:177], v[210:211], v[178:179]
	v_pk_fma_f32 v[190:191], v[180:181], v[212:213], v[182:183]
	v_pk_fma_f32 v[192:193], v[200:201], v[192:193], v[202:203]
	v_pk_fma_f32 v[140:141], v[140:141], 0.5, v[188:189] op_sel_hi:[1,0,1]
	v_pk_mul_f32 v[186:187], v[194:195], s[94:95] op_sel_hi:[1,0]
	v_pk_fma_f32 v[142:143], v[142:143], 0.5, v[190:191] op_sel_hi:[1,0,1]
	v_pk_fma_f32 v[190:191], v[138:139], 0.5, v[192:193] op_sel_hi:[1,0,1]
	v_pk_add_f32 v[138:139], v[140:141], 0 op_sel_hi:[1,0]
	v_pk_fma_f32 v[194:195], v[184:185], v[214:215], v[186:187]
	v_pk_add_f32 v[192:193], v[142:143], v[138:139]
	v_pk_mul_f32 v[138:139], v[142:143], v[142:143]
	v_pk_fma_f32 v[188:189], v[136:137], 0.5, v[194:195] op_sel_hi:[1,0,1]
	v_cvt_pk_f16_f32 v136, v140, v141
	v_pk_fma_f32 v[140:141], v[140:141], v[140:141], v[138:139]
	v_cvt_pk_f16_f32 v137, v142, v143
	v_cvt_pk_f16_f32 v138, v188, v189
	v_pk_add_f32 v[142:143], v[188:189], v[192:193]
	v_pk_fma_f32 v[140:141], v[188:189], v[188:189], v[140:141]
	v_add_u32_e32 v188, v206, v174
	v_mov_b32_e32 v189, v3
	v_cvt_pk_f16_f32 v139, v190, v191
	v_pk_add_f32 v[142:143], v[190:191], v[142:143]
	v_lshl_add_u64 v[188:189], v[188:189], 1, s[12:13]
	global_store_dwordx4 v[188:189], v[136:139], off
	v_pk_fma_f32 v[140:141], v[190:191], v[190:191], v[140:141]
	s_nop 0
	v_pk_add_f32 v[136:137], v[142:143], v[142:143] op_sel:[0,1] op_sel_hi:[1,0]
	v_pk_add_f32 v[142:143], v[140:141], v[140:141] op_sel:[0,1] op_sel_hi:[1,0]
	v_mov_b32_e32 v137, v136
	s_nop 1
	v_permlane16_swap_b32_e32 v136, v137
	v_add_f32_e32 v138, v136, v137
	v_mov_b32_e32 v136, v142
	s_nop 1
	v_permlane16_swap_b32_e32 v142, v136
	v_add_f32_e32 v139, v142, v136
	v_mov_b32_e32 v140, v138
	v_mov_b32_e32 v141, v139
	s_nop 0
	v_permlane32_swap_b32_e32 v138, v140
	v_permlane32_swap_b32_e32 v139, v141
	v_lshlrev_b32_e32 v136, 6, v207
	s_mov_b64 s[26:27], exec
	s_and_b64 s[28:29], s[26:27], vcc
	s_mov_b32 s88, 0x48000
	s_mov_b32 s80, 0x50000
	v_mov_b32_e32 v248, v252
	v_mov_b32_e32 v249, v253
	v_mov_b64_e32 v[250:251], 0x1ff
	v_mov_b64_e32 v[244:245], 0xaff
	s_mov_b64 exec, s[28:29]
	s_cbranch_execz .LBB0_612
	s_lshl_b32 s1, s57, 4
	v_mov_b32_e32 v137, v3
	s_or_b32 s28, s1, s64
	v_pk_add_f32 v[138:139], v[138:139], v[140:141]
	v_lshl_add_u64 v[140:141], v[136:137], 2, s[14:15]
	s_ashr_i32 s29, s28, 31
	v_lshl_add_u64 v[140:141], s[28:29], 2, v[140:141]
	global_store_dwordx2 v[140:141], v[138:139], off

.LBB0_626:
	s_or_b64 exec, exec, s[26:27]
	v_add_u32_e32 v68, 0x20080, v2
	v_mov_b32_e32 v69, v3
	v_lshl_add_u64 v[68:69], v[68:69], 1, s[10:11]
	global_load_dwordx4 v[84:87], v[68:69], off
	v_add_u32_e32 v68, 0x24080, v2
	v_mov_b32_e32 v69, v3
	v_lshl_add_u64 v[68:69], v[68:69], 1, s[10:11]
	global_load_dwordx4 v[80:83], v[68:69], off
	v_add_u32_e32 v68, 0x28080, v2
	v_mov_b32_e32 v69, v3
	v_lshl_add_u64 v[68:69], v[68:69], 1, s[10:11]
	v_add_u32_e32 v2, 0x2c080, v2
	global_load_dwordx4 v[72:75], v[68:69], off
	v_lshl_add_u64 v[68:69], v[2:3], 1, s[10:11]
	global_load_dwordx4 v[68:71], v[68:69], off
	s_nop 0
	v_mov_b64_e32 v[108:109], v[216:217]
	v_mov_b64_e32 v[110:111], v[218:219]
	v_mov_b64_e32 v[112:113], v[220:221]
	v_mov_b64_e32 v[114:115], v[222:223]
	s_waitcnt vmcnt(11)
	v_lshlrev_b32_e32 v142, 16, v116
	v_and_b32_e32 v143, 0xffff0000, v116
	v_lshlrev_b32_e32 v116, 16, v117
	v_and_b32_e32 v117, 0xffff0000, v117
	v_lshlrev_b32_e32 v144, 16, v118
	v_and_b32_e32 v145, 0xffff0000, v118
	v_lshlrev_b32_e32 v118, 16, v119
	v_and_b32_e32 v119, 0xffff0000, v119
	v_add_u32_e32 v97, 0x80, v174
	v_pk_mul_f32 v[110:111], v[110:111], s[94:95] op_sel_hi:[1,0]
	v_pk_mul_f32 v[98:99], v[112:113], s[94:95] op_sel_hi:[1,0]
	v_pk_mul_f32 v[106:107], v[114:115], s[94:95] op_sel_hi:[1,0]
	v_mov_b64_e32 v[120:121], v[224:225]
	v_mov_b64_e32 v[122:123], v[226:227]
	v_mov_b64_e32 v[112:113], v[228:229]
	v_mov_b64_e32 v[114:115], v[230:231]
	ds_read_b64 v[140:141], v175
	v_pk_mul_f32 v[108:109], v[108:109], s[94:95] op_sel_hi:[1,0]
	s_waitcnt lgkmcnt(0)
	v_mul_f32_e64 v2, v141, -v140
	v_pk_fma_f32 v[142:143], v[140:141], v[142:143], v[2:3] op_sel:[1,0,0] op_sel_hi:[1,1,0]
	v_pk_fma_f32 v[116:117], v[140:141], v[116:117], v[2:3] op_sel:[1,0,0] op_sel_hi:[1,1,0]
	v_pk_fma_f32 v[144:145], v[140:141], v[144:145], v[2:3] op_sel:[1,0,0] op_sel_hi:[1,1,0]
	v_pk_fma_f32 v[118:119], v[140:141], v[118:119], v[2:3] op_sel:[1,0,0] op_sel_hi:[1,1,0]
	v_add_u32_e32 v2, v97, v206
	v_pk_mul_f32 v[122:123], v[122:123], s[94:95] op_sel_hi:[1,0]
	v_pk_mul_f32 v[112:113], v[112:113], s[94:95] op_sel_hi:[1,0]
	v_pk_mul_f32 v[114:115], v[114:115], s[94:95] op_sel_hi:[1,0]
	v_pk_fma_f32 v[140:141], v[112:113], v[142:143], v[98:99]
	v_pk_mul_f32 v[120:121], v[120:121], s[94:95] op_sel_hi:[1,0]
	v_pk_fma_f32 v[116:117], v[114:115], v[116:117], v[106:107]
	v_pk_fma_f32 v[118:119], v[122:123], v[118:119], v[110:111]
	v_pk_fma_f32 v[64:65], v[64:65], 0.5, v[140:141] op_sel_hi:[1,0,1]
	v_pk_fma_f32 v[142:143], v[120:121], v[144:145], v[108:109]
	v_pk_fma_f32 v[66:67], v[66:67], 0.5, v[116:117] op_sel_hi:[1,0,1]
	v_pk_fma_f32 v[118:119], v[62:63], 0.5, v[118:119] op_sel_hi:[1,0,1]
	v_pk_add_f32 v[62:63], v[64:65], 0 op_sel_hi:[1,0]
	v_pk_fma_f32 v[116:117], v[60:61], 0.5, v[142:143] op_sel_hi:[1,0,1]
	v_pk_add_f32 v[140:141], v[66:67], v[62:63]
	v_pk_mul_f32 v[62:63], v[66:67], v[66:67]
	v_cvt_pk_f16_f32 v60, v64, v65
	v_cvt_pk_f16_f32 v61, v66, v67
	v_pk_fma_f32 v[64:65], v[64:65], v[64:65], v[62:63]
	v_pk_add_f32 v[66:67], v[116:117], v[140:141]
	v_cvt_pk_f16_f32 v62, v116, v117
	v_pk_fma_f32 v[64:65], v[116:117], v[116:117], v[64:65]
	v_cvt_pk_f16_f32 v63, v118, v119
	v_pk_add_f32 v[66:67], v[118:119], v[66:67]
	v_lshl_add_u64 v[116:117], v[2:3], 1, s[12:13]
	global_store_dwordx4 v[116:117], v[60:63], off
	v_pk_fma_f32 v[64:65], v[118:119], v[118:119], v[64:65]
	s_nop 0
	v_pk_add_f32 v[60:61], v[66:67], v[66:67] op_sel:[0,1] op_sel_hi:[1,0]
	v_pk_add_f32 v[64:65], v[64:65], v[64:65] op_sel:[0,1] op_sel_hi:[1,0]
	v_mov_b32_e32 v2, v60
	s_nop 1
	v_permlane16_swap_b32_e32 v60, v2
	v_add_f32_e32 v60, v60, v2
	v_mov_b32_e32 v2, v64
	s_nop 1
	v_permlane16_swap_b32_e32 v64, v2
	v_add_f32_e32 v61, v64, v2
	v_mov_b32_e32 v62, v60
	v_mov_b32_e32 v63, v61
	s_nop 0
	v_permlane32_swap_b32_e32 v60, v62
	v_permlane32_swap_b32_e32 v61, v63
	s_and_saveexec_b64 s[26:27], vcc
	s_cbranch_execz .LBB0_628
	s_lshl_b32 s0, s57, 4
	v_mov_b32_e32 v137, v3
	s_ashr_i32 s1, s0, 31
	v_pk_add_f32 v[60:61], v[60:61], v[62:63]
	v_lshl_add_u64 v[62:63], v[136:137], 2, s[14:15]
	s_or_b64 s[0:1], s[0:1], s[64:65]
	v_lshl_add_u64 v[62:63], s[0:1], 2, v[62:63]
	global_store_dwordx2 v[62:63], v[60:61], off offset:32
.LBB0_628:
	s_or_b64 exec, exec, s[26:27]
	s_waitcnt vmcnt(9)
	ds_read_b64 v[60:61], v175 offset:128
	v_lshlrev_b32_e32 v62, 16, v100
	v_and_b32_e32 v63, 0xffff0000, v100
	v_lshlrev_b32_e32 v64, 16, v101
	v_and_b32_e32 v65, 0xffff0000, v101
	s_waitcnt lgkmcnt(0)
	v_mul_f32_e64 v2, v61, -v60
	v_pk_fma_f32 v[62:63], v[60:61], v[62:63], v[2:3] op_sel:[1,0,0] op_sel_hi:[1,1,0]
	v_lshlrev_b32_e32 v66, 16, v102
	v_and_b32_e32 v67, 0xffff0000, v102
	v_lshlrev_b32_e32 v100, 16, v103
	v_and_b32_e32 v101, 0xffff0000, v103
	v_pk_fma_f32 v[64:65], v[60:61], v[64:65], v[2:3] op_sel:[1,0,0] op_sel_hi:[1,1,0]
	v_pk_fma_f32 v[66:67], v[60:61], v[66:67], v[2:3] op_sel:[1,0,0] op_sel_hi:[1,1,0]
	v_pk_fma_f32 v[60:61], v[60:61], v[100:101], v[2:3] op_sel:[1,0,0] op_sel_hi:[1,1,0]
	v_pk_fma_f32 v[62:63], v[112:113], v[62:63], v[98:99]
	v_pk_fma_f32 v[64:65], v[114:115], v[64:65], v[106:107]
	v_pk_fma_f32 v[60:61], v[122:123], v[60:61], v[110:111]
	v_pk_fma_f32 v[56:57], v[56:57], 0.5, v[62:63] op_sel_hi:[1,0,1]
	v_pk_fma_f32 v[58:59], v[58:59], 0.5, v[64:65] op_sel_hi:[1,0,1]
	v_pk_fma_f32 v[60:61], v[54:55], 0.5, v[60:61] op_sel_hi:[1,0,1]
	v_pk_add_f32 v[54:55], v[56:57], 0 op_sel_hi:[1,0]
	v_pk_fma_f32 v[66:67], v[120:121], v[66:67], v[108:109]
	v_pk_add_f32 v[64:65], v[58:59], v[54:55]
	v_pk_mul_f32 v[54:55], v[58:59], v[58:59]
	v_pk_fma_f32 v[62:63], v[52:53], 0.5, v[66:67] op_sel_hi:[1,0,1]
	v_cvt_pk_f16_f32 v52, v56, v57
	v_pk_fma_f32 v[56:57], v[56:57], v[56:57], v[54:55]
	v_cvt_pk_f16_f32 v53, v58, v59
	v_pk_add_f32 v[58:59], v[62:63], v[64:65]
	v_pk_fma_f32 v[56:57], v[62:63], v[62:63], v[56:57]
	v_add_u32_e32 v2, v138, v97
	v_cvt_pk_f16_f32 v54, v62, v63
	v_cvt_pk_f16_f32 v55, v60, v61
	v_pk_add_f32 v[58:59], v[60:61], v[58:59]
	v_pk_fma_f32 v[56:57], v[60:61], v[60:61], v[56:57]
	v_lshl_add_u64 v[60:61], v[2:3], 1, s[12:13]
	global_store_dwordx4 v[60:61], v[52:55], off
	v_pk_add_f32 v[56:57], v[56:57], v[56:57] op_sel:[0,1] op_sel_hi:[1,0]
	s_nop 0
	v_pk_add_f32 v[52:53], v[58:59], v[58:59] op_sel:[0,1] op_sel_hi:[1,0]
	s_nop 0
	v_mov_b32_e32 v2, v52
	s_nop 1
	v_permlane16_swap_b32_e32 v52, v2
	v_add_f32_e32 v52, v52, v2
	v_mov_b32_e32 v2, v56
	s_nop 1
	v_permlane16_swap_b32_e32 v56, v2
	v_add_f32_e32 v53, v56, v2
	v_mov_b32_e32 v54, v52
	v_mov_b32_e32 v55, v53
	s_nop 0
	v_permlane32_swap_b32_e32 v52, v54
	v_permlane32_swap_b32_e32 v53, v55
	s_and_saveexec_b64 s[26:27], vcc
	s_cbranch_execz .LBB0_630
	s_lshl_b32 s0, s57, 4
	v_mov_b32_e32 v125, v3
	s_ashr_i32 s1, s0, 31
	v_pk_add_f32 v[52:53], v[52:53], v[54:55]
	v_lshl_add_u64 v[54:55], v[124:125], 2, s[14:15]
	s_or_b64 s[0:1], s[0:1], s[64:65]
	v_lshl_add_u64 v[54:55], s[0:1], 2, v[54:55]
	global_store_dwordx2 v[54:55], v[52:53], off offset:32

.LBB0_634:
	s_or_b64 exec, exec, s[26:27]
	s_waitcnt vmcnt(4)
	ds_read_b64 v[36:37], v175 offset:1024
	v_lshlrev_b32_e32 v38, 16, v84
	v_and_b32_e32 v39, 0xffff0000, v84
	v_lshlrev_b32_e32 v40, 16, v85
	v_and_b32_e32 v41, 0xffff0000, v85
	s_waitcnt lgkmcnt(0)
	v_mul_f32_e64 v2, v37, -v36
	v_pk_fma_f32 v[38:39], v[36:37], v[38:39], v[2:3] op_sel:[1,0,0] op_sel_hi:[1,1,0]
	v_lshlrev_b32_e32 v42, 16, v86
	v_and_b32_e32 v43, 0xffff0000, v86
	v_lshlrev_b32_e32 v44, 16, v87
	v_and_b32_e32 v45, 0xffff0000, v87
	v_pk_fma_f32 v[40:41], v[36:37], v[40:41], v[2:3] op_sel:[1,0,0] op_sel_hi:[1,1,0]
	v_pk_fma_f32 v[42:43], v[36:37], v[42:43], v[2:3] op_sel:[1,0,0] op_sel_hi:[1,1,0]
	v_pk_fma_f32 v[36:37], v[36:37], v[44:45], v[2:3] op_sel:[1,0,0] op_sel_hi:[1,1,0]
	v_pk_fma_f32 v[38:39], v[112:113], v[38:39], v[98:99]
	v_pk_fma_f32 v[40:41], v[114:115], v[40:41], v[106:107]
	v_pk_fma_f32 v[36:37], v[122:123], v[36:37], v[110:111]
	v_pk_fma_f32 v[32:33], v[32:33], 0.5, v[38:39] op_sel_hi:[1,0,1]
	v_pk_fma_f32 v[34:35], v[34:35], 0.5, v[40:41] op_sel_hi:[1,0,1]
	v_pk_fma_f32 v[36:37], v[30:31], 0.5, v[36:37] op_sel_hi:[1,0,1]
	v_pk_add_f32 v[30:31], v[32:33], 0 op_sel_hi:[1,0]
	v_pk_fma_f32 v[42:43], v[120:121], v[42:43], v[108:109]
	v_pk_add_f32 v[40:41], v[34:35], v[30:31]
	v_pk_mul_f32 v[30:31], v[34:35], v[34:35]
	v_pk_fma_f32 v[38:39], v[28:29], 0.5, v[42:43] op_sel_hi:[1,0,1]
	v_cvt_pk_f16_f32 v28, v32, v33
	v_pk_fma_f32 v[32:33], v[32:33], v[32:33], v[30:31]
	v_cvt_pk_f16_f32 v29, v34, v35
	v_pk_add_f32 v[34:35], v[38:39], v[40:41]
	v_pk_fma_f32 v[32:33], v[38:39], v[38:39], v[32:33]
	v_add_u32_e32 v2, v139, v97
	v_cvt_pk_f16_f32 v30, v38, v39
	v_cvt_pk_f16_f32 v31, v36, v37
	v_pk_add_f32 v[34:35], v[36:37], v[34:35]
	v_pk_fma_f32 v[32:33], v[36:37], v[36:37], v[32:33]
	v_lshl_add_u64 v[36:37], v[2:3], 1, s[12:13]
	global_store_dwordx4 v[36:37], v[28:31], off
	v_pk_add_f32 v[32:33], v[32:33], v[32:33] op_sel:[0,1] op_sel_hi:[1,0]
	s_nop 0
	v_pk_add_f32 v[28:29], v[34:35], v[34:35] op_sel:[0,1] op_sel_hi:[1,0]
	s_nop 0
	v_mov_b32_e32 v2, v28
	s_nop 1
	v_permlane16_swap_b32_e32 v28, v2
	v_add_f32_e32 v28, v28, v2
	v_mov_b32_e32 v2, v32
	s_nop 1
	v_permlane16_swap_b32_e32 v32, v2
	v_add_f32_e32 v29, v32, v2
	v_mov_b32_e32 v30, v28
	v_mov_b32_e32 v31, v29
	s_nop 0
	v_permlane32_swap_b32_e32 v28, v30
	v_permlane32_swap_b32_e32 v29, v31
	s_and_saveexec_b64 s[26:27], vcc
	s_cbranch_execz .LBB0_636
	s_lshl_b32 s0, s57, 4
	v_mov_b32_e32 v105, v3
	s_ashr_i32 s1, s0, 31
	v_pk_add_f32 v[28:29], v[28:29], v[30:31]
	v_lshl_add_u64 v[30:31], v[104:105], 2, s[14:15]
	s_or_b64 s[0:1], s[0:1], s[64:65]
	v_lshl_add_u64 v[30:31], s[0:1], 2, v[30:31]
	global_store_dwordx2 v[30:31], v[28:29], off offset:32

.LBB0_1766:
	s_lshl_b32 s1, s56, 8
	v_mbcnt_lo_u32_b32 v198, -1, 0
	v_mbcnt_hi_u32_b32 v198, -1, v198
	s_lshl_b32 s0, s49, 18
	v_and_or_b32 v208, v198, 15, s50
	v_ashrrev_i32_e32 v112, 1, v198
	s_or_b32 s1, s1, s51
	v_lshlrev_b32_e32 v2, 10, v208
	v_and_b32_e32 v112, -8, v112
	s_add_i32 s0, s1, s0
	v_add3_u32 v2, s0, v112, v2
	v_add_u32_e32 v174, s1, v112
	v_lshl_add_u64 v[148:149], v[2:3], 1, s[8:9]
	v_ashrrev_i32_e32 v175, 31, v174
	global_load_dwordx4 v[176:179], v[148:149], off
	v_lshlrev_b64 v[112:113], 2, v[174:175]
	v_lshl_add_u64 v[170:171], s[14:15], 0, v[112:113]
	v_lshl_add_u64 v[172:173], s[16:17], 0, v[112:113]
	global_load_dwordx4 v[180:183], v[170:171], off
	global_load_dwordx4 v[184:187], v[172:173], off
	global_load_dwordx4 v[188:191], v[170:171], off offset:16
	global_load_dwordx4 v[192:195], v[172:173], off offset:16
	global_load_dwordx4 v[216:219], v[172:173], off offset:528
	global_load_dwordx4 v[220:223], v[172:173], off offset:512
	global_load_dwordx4 v[224:227], v[170:171], off offset:528
	global_load_dwordx4 v[228:231], v[170:171], off offset:512
	v_add_co_u32_e32 v150, vcc, 0x8000, v148
	v_mov_b32_e32 v113, v3
	v_mov_b32_e32 v115, v3
	v_mov_b32_e32 v121, v3
	v_add_u32_e32 v112, 0x20000, v2
	v_add_u32_e32 v114, 0x24000, v2
	v_add_u32_e32 v120, 0x28000, v2
	v_addc_co_u32_e32 v151, vcc, 0, v149, vcc
	s_mov_b32 s79, 0x10000
	v_mov_b32_e32 v123, v3
	v_add_u32_e32 v122, 0x2c000, v2
	v_lshl_add_u64 v[112:113], v[112:113], 1, s[8:9]
	v_lshl_add_u64 v[114:115], v[114:115], 1, s[8:9]
	v_lshl_add_u64 v[120:121], v[120:121], 1, s[8:9]
	v_add_co_u32_e32 v154, vcc, s79, v148
	v_lshl_add_u64 v[152:153], v[122:123], 1, s[8:9]
	global_load_dwordx4 v[144:147], v[112:113], off
	global_load_dwordx4 v[132:135], v[114:115], off
	s_nop 0
	global_load_dwordx4 v[120:123], v[120:121], off
	s_nop 0
	global_load_dwordx4 v[112:115], v[152:153], off
	global_load_dwordx4 v[156:159], v[150:151], off
	v_addc_co_u32_e32 v155, vcc, 0, v149, vcc
	v_add_co_u32_e32 v148, vcc, s92, v148
	s_lshl_b32 s0, s58, 11
	s_nop 0
	v_addc_co_u32_e32 v149, vcc, 0, v149, vcc
	global_load_dwordx4 v[152:155], v[154:155], off
	s_nop 0
	global_load_dwordx4 v[148:151], v[148:149], off
	s_add_i32 s0, s0, 0
	v_lshl_add_u32 v175, v208, 3, s0
	v_add_u32_e32 v175, 0x20200, v175
	ds_read_b64 v[196:197], v175
	v_cmp_gt_u32_e32 vcc, 16, v198
	s_lshl_b32 s0, s49, 8
	v_add_u32_e32 v207, s0, v208
	v_lshlrev_b32_e32 v206, 10, v207
	s_waitcnt lgkmcnt(0)
	v_mul_f32_e64 v198, v197, -v196
	s_waitcnt vmcnt(0)
	v_lshlrev_b32_e32 v200, 16, v176
	v_and_b32_e32 v201, 0xffff0000, v176
	v_lshlrev_b32_e32 v176, 16, v177
	v_and_b32_e32 v177, 0xffff0000, v177
	v_lshlrev_b32_e32 v202, 16, v178
	v_and_b32_e32 v203, 0xffff0000, v178
	v_lshlrev_b32_e32 v178, 16, v179
	v_and_b32_e32 v179, 0xffff0000, v179
	v_pk_fma_f32 v[210:211], v[196:197], v[200:201], v[198:199] op_sel:[1,0,0] op_sel_hi:[1,1,0]
	v_pk_fma_f32 v[212:213], v[196:197], v[176:177], v[198:199] op_sel:[1,0,0] op_sel_hi:[1,1,0]
	v_pk_fma_f32 v[214:215], v[196:197], v[202:203], v[198:199] op_sel:[1,0,0] op_sel_hi:[1,1,0]
	v_pk_fma_f32 v[196:197], v[196:197], v[178:179], v[198:199] op_sel:[1,0,0] op_sel_hi:[1,1,0]
	v_pk_mul_f32 v[176:177], v[180:181], s[94:95] op_sel_hi:[1,0]
	v_pk_mul_f32 v[178:179], v[184:185], s[94:95] op_sel_hi:[1,0]
	v_pk_mul_f32 v[180:181], v[182:183], s[94:95] op_sel_hi:[1,0]
	v_pk_mul_f32 v[182:183], v[186:187], s[94:95] op_sel_hi:[1,0]
	v_pk_mul_f32 v[184:185], v[188:189], s[94:95] op_sel_hi:[1,0]
	v_pk_mul_f32 v[200:201], v[190:191], s[94:95] op_sel_hi:[1,0]
	v_pk_mul_f32 v[202:203], v[194:195], s[94:95] op_sel_hi:[1,0]
	v_pk_fma_f32 v[188:189], v[176:177], v[210:211], v[178:179]
	v_pk_mul_f32 v[186:187], v[192:193], s[94:95] op_sel_hi:[1,0]
	v_pk_fma_f32 v[190:191], v[180:181], v[212:213], v[182:183]
	v_pk_fma_f32 v[194:195], v[200:201], v[196:197], v[202:203]
	v_pk_fma_f32 v[140:141], v[140:141], 0.5, v[188:189] op_sel_hi:[1,0,1]
	v_pk_fma_f32 v[192:193], v[184:185], v[214:215], v[186:187]
	v_pk_fma_f32 v[142:143], v[142:143], 0.5, v[190:191] op_sel_hi:[1,0,1]
	v_pk_fma_f32 v[190:191], v[138:139], 0.5, v[194:195] op_sel_hi:[1,0,1]
	v_pk_add_f32 v[138:139], v[140:141], 0 op_sel_hi:[1,0]
	v_pk_fma_f32 v[188:189], v[136:137], 0.5, v[192:193] op_sel_hi:[1,0,1]
	v_pk_add_f32 v[192:193], v[142:143], v[138:139]
	v_pk_mul_f32 v[138:139], v[142:143], v[142:143]
	v_cvt_pk_f16_f32 v136, v140, v141
	v_pk_fma_f32 v[140:141], v[140:141], v[140:141], v[138:139]
	v_cvt_pk_f16_f32 v137, v142, v143
	v_cvt_pk_f16_f32 v138, v188, v189
	v_pk_add_f32 v[142:143], v[188:189], v[192:193]
	v_pk_fma_f32 v[140:141], v[188:189], v[188:189], v[140:141]
	v_add_u32_e32 v188, v206, v174
	v_mov_b32_e32 v189, v3
	v_cvt_pk_f16_f32 v139, v190, v191
	v_pk_add_f32 v[142:143], v[190:191], v[142:143]
	v_lshl_add_u64 v[188:189], v[188:189], 1, s[10:11]
	global_store_dwordx4 v[188:189], v[136:139], off
	v_pk_fma_f32 v[140:141], v[190:191], v[190:191], v[140:141]
	s_nop 0
	v_pk_add_f32 v[136:137], v[142:143], v[142:143] op_sel:[0,1] op_sel_hi:[1,0]
	v_pk_add_f32 v[142:143], v[140:141], v[140:141] op_sel:[0,1] op_sel_hi:[1,0]
	v_mov_b32_e32 v137, v136
	s_nop 1
	v_permlane16_swap_b32_e32 v136, v137
	v_add_f32_e32 v138, v136, v137
	v_mov_b32_e32 v136, v142
	s_nop 1
	v_permlane16_swap_b32_e32 v142, v136
	v_add_f32_e32 v139, v142, v136
	v_mov_b32_e32 v140, v138
	v_mov_b32_e32 v141, v139
	s_nop 0
	v_permlane32_swap_b32_e32 v138, v140
	v_permlane32_swap_b32_e32 v139, v141
	v_lshlrev_b32_e32 v136, 6, v207
	s_mov_b64 s[24:25], exec
	s_and_b64 s[26:27], s[24:25], vcc
	s_mov_b32 s80, 0x50000
	v_mov_b32_e32 v248, v252
	v_mov_b32_e32 v249, v253
	v_mov_b64_e32 v[250:251], 0x1ff
	v_mov_b64_e32 v[244:245], 0xaff
	s_mov_b64 exec, s[26:27]
	s_cbranch_execz .LBB0_1768
	s_lshl_b32 s1, s56, 4
	v_mov_b32_e32 v137, v3
	s_or_b32 s26, s1, s64
	v_pk_add_f32 v[138:139], v[138:139], v[140:141]
	v_lshl_add_u64 v[140:141], v[136:137], 2, s[12:13]
	s_ashr_i32 s27, s26, 31
	v_lshl_add_u64 v[140:141], s[26:27], 2, v[140:141]
	global_store_dwordx2 v[140:141], v[138:139], off

.LBB0_1782:
	s_or_b64 exec, exec, s[24:25]
	v_add_u32_e32 v68, 0x20080, v2
	v_mov_b32_e32 v69, v3
	v_lshl_add_u64 v[68:69], v[68:69], 1, s[8:9]
	global_load_dwordx4 v[84:87], v[68:69], off
	v_add_u32_e32 v68, 0x24080, v2
	v_mov_b32_e32 v69, v3
	v_lshl_add_u64 v[68:69], v[68:69], 1, s[8:9]
	global_load_dwordx4 v[80:83], v[68:69], off
	v_add_u32_e32 v68, 0x28080, v2
	v_mov_b32_e32 v69, v3
	v_lshl_add_u64 v[68:69], v[68:69], 1, s[8:9]
	v_add_u32_e32 v2, 0x2c080, v2
	global_load_dwordx4 v[72:75], v[68:69], off
	v_lshl_add_u64 v[68:69], v[2:3], 1, s[8:9]
	global_load_dwordx4 v[68:71], v[68:69], off
	s_nop 0
	v_mov_b64_e32 v[108:109], v[216:217]
	v_mov_b64_e32 v[110:111], v[218:219]
	v_mov_b64_e32 v[112:113], v[220:221]
	v_mov_b64_e32 v[114:115], v[222:223]
	s_waitcnt vmcnt(11)
	v_lshlrev_b32_e32 v142, 16, v116
	v_and_b32_e32 v143, 0xffff0000, v116
	v_lshlrev_b32_e32 v116, 16, v117
	v_and_b32_e32 v117, 0xffff0000, v117
	v_lshlrev_b32_e32 v144, 16, v118
	v_and_b32_e32 v145, 0xffff0000, v118
	v_lshlrev_b32_e32 v118, 16, v119
	v_and_b32_e32 v119, 0xffff0000, v119
	v_add_u32_e32 v97, 0x80, v174
	v_pk_mul_f32 v[110:111], v[110:111], s[94:95] op_sel_hi:[1,0]
	v_pk_mul_f32 v[98:99], v[112:113], s[94:95] op_sel_hi:[1,0]
	v_pk_mul_f32 v[106:107], v[114:115], s[94:95] op_sel_hi:[1,0]
	v_mov_b64_e32 v[120:121], v[224:225]
	v_mov_b64_e32 v[122:123], v[226:227]
	v_mov_b64_e32 v[112:113], v[228:229]
	v_mov_b64_e32 v[114:115], v[230:231]
	ds_read_b64 v[140:141], v175
	v_pk_mul_f32 v[108:109], v[108:109], s[94:95] op_sel_hi:[1,0]
	s_waitcnt lgkmcnt(0)
	v_mul_f32_e64 v2, v141, -v140
	v_pk_fma_f32 v[142:143], v[140:141], v[142:143], v[2:3] op_sel:[1,0,0] op_sel_hi:[1,1,0]
	v_pk_fma_f32 v[116:117], v[140:141], v[116:117], v[2:3] op_sel:[1,0,0] op_sel_hi:[1,1,0]
	v_pk_fma_f32 v[144:145], v[140:141], v[144:145], v[2:3] op_sel:[1,0,0] op_sel_hi:[1,1,0]
	v_pk_fma_f32 v[118:119], v[140:141], v[118:119], v[2:3] op_sel:[1,0,0] op_sel_hi:[1,1,0]
	v_add_u32_e32 v2, v97, v206
	v_pk_mul_f32 v[122:123], v[122:123], s[94:95] op_sel_hi:[1,0]
	v_pk_mul_f32 v[112:113], v[112:113], s[94:95] op_sel_hi:[1,0]
	v_pk_mul_f32 v[114:115], v[114:115], s[94:95] op_sel_hi:[1,0]
	v_pk_fma_f32 v[140:141], v[112:113], v[142:143], v[98:99]
	v_pk_mul_f32 v[120:121], v[120:121], s[94:95] op_sel_hi:[1,0]
	v_pk_fma_f32 v[116:117], v[114:115], v[116:117], v[106:107]
	v_pk_fma_f32 v[118:119], v[122:123], v[118:119], v[110:111]
	v_pk_fma_f32 v[64:65], v[64:65], 0.5, v[140:141] op_sel_hi:[1,0,1]
	v_pk_fma_f32 v[142:143], v[120:121], v[144:145], v[108:109]
	v_pk_fma_f32 v[66:67], v[66:67], 0.5, v[116:117] op_sel_hi:[1,0,1]
	v_pk_fma_f32 v[118:119], v[62:63], 0.5, v[118:119] op_sel_hi:[1,0,1]
	v_pk_add_f32 v[62:63], v[64:65], 0 op_sel_hi:[1,0]
	v_pk_fma_f32 v[116:117], v[60:61], 0.5, v[142:143] op_sel_hi:[1,0,1]
	v_pk_add_f32 v[140:141], v[66:67], v[62:63]
	v_pk_mul_f32 v[62:63], v[66:67], v[66:67]
	v_cvt_pk_f16_f32 v60, v64, v65
	v_cvt_pk_f16_f32 v61, v66, v67
	v_pk_fma_f32 v[64:65], v[64:65], v[64:65], v[62:63]
	v_pk_add_f32 v[66:67], v[116:117], v[140:141]
	v_cvt_pk_f16_f32 v62, v116, v117
	v_pk_fma_f32 v[64:65], v[116:117], v[116:117], v[64:65]
	v_cvt_pk_f16_f32 v63, v118, v119
	v_pk_add_f32 v[66:67], v[118:119], v[66:67]
	v_lshl_add_u64 v[116:117], v[2:3], 1, s[10:11]
	global_store_dwordx4 v[116:117], v[60:63], off
	v_pk_fma_f32 v[64:65], v[118:119], v[118:119], v[64:65]
	s_nop 0
	v_pk_add_f32 v[60:61], v[66:67], v[66:67] op_sel:[0,1] op_sel_hi:[1,0]
	v_pk_add_f32 v[64:65], v[64:65], v[64:65] op_sel:[0,1] op_sel_hi:[1,0]
	v_mov_b32_e32 v2, v60
	s_nop 1
	v_permlane16_swap_b32_e32 v60, v2
	v_add_f32_e32 v60, v60, v2
	v_mov_b32_e32 v2, v64
	s_nop 1
	v_permlane16_swap_b32_e32 v64, v2
	v_add_f32_e32 v61, v64, v2
	v_mov_b32_e32 v62, v60
	v_mov_b32_e32 v63, v61
	s_nop 0
	v_permlane32_swap_b32_e32 v60, v62
	v_permlane32_swap_b32_e32 v61, v63
	s_and_saveexec_b64 s[24:25], vcc
	s_cbranch_execz .LBB0_1784
	s_lshl_b32 s0, s56, 4
	v_mov_b32_e32 v137, v3
	s_ashr_i32 s1, s0, 31
	v_pk_add_f32 v[60:61], v[60:61], v[62:63]
	v_lshl_add_u64 v[62:63], v[136:137], 2, s[12:13]
	s_or_b64 s[0:1], s[0:1], s[64:65]
	v_lshl_add_u64 v[62:63], s[0:1], 2, v[62:63]
	global_store_dwordx2 v[62:63], v[60:61], off offset:32
.LBB0_1784:
	s_or_b64 exec, exec, s[24:25]
	s_waitcnt vmcnt(9)
	ds_read_b64 v[60:61], v175 offset:128
	v_lshlrev_b32_e32 v62, 16, v100
	v_and_b32_e32 v63, 0xffff0000, v100
	v_lshlrev_b32_e32 v64, 16, v101
	v_and_b32_e32 v65, 0xffff0000, v101
	s_waitcnt lgkmcnt(0)
	v_mul_f32_e64 v2, v61, -v60
	v_pk_fma_f32 v[62:63], v[60:61], v[62:63], v[2:3] op_sel:[1,0,0] op_sel_hi:[1,1,0]
	v_lshlrev_b32_e32 v66, 16, v102
	v_and_b32_e32 v67, 0xffff0000, v102
	v_lshlrev_b32_e32 v100, 16, v103
	v_and_b32_e32 v101, 0xffff0000, v103
	v_pk_fma_f32 v[64:65], v[60:61], v[64:65], v[2:3] op_sel:[1,0,0] op_sel_hi:[1,1,0]
	v_pk_fma_f32 v[66:67], v[60:61], v[66:67], v[2:3] op_sel:[1,0,0] op_sel_hi:[1,1,0]
	v_pk_fma_f32 v[60:61], v[60:61], v[100:101], v[2:3] op_sel:[1,0,0] op_sel_hi:[1,1,0]
	v_pk_fma_f32 v[62:63], v[112:113], v[62:63], v[98:99]
	v_pk_fma_f32 v[64:65], v[114:115], v[64:65], v[106:107]
	v_pk_fma_f32 v[60:61], v[122:123], v[60:61], v[110:111]
	v_pk_fma_f32 v[56:57], v[56:57], 0.5, v[62:63] op_sel_hi:[1,0,1]
	v_pk_fma_f32 v[58:59], v[58:59], 0.5, v[64:65] op_sel_hi:[1,0,1]
	v_pk_fma_f32 v[60:61], v[54:55], 0.5, v[60:61] op_sel_hi:[1,0,1]
	v_pk_add_f32 v[54:55], v[56:57], 0 op_sel_hi:[1,0]
	v_pk_fma_f32 v[66:67], v[120:121], v[66:67], v[108:109]
	v_pk_add_f32 v[64:65], v[58:59], v[54:55]
	v_pk_mul_f32 v[54:55], v[58:59], v[58:59]
	v_pk_fma_f32 v[62:63], v[52:53], 0.5, v[66:67] op_sel_hi:[1,0,1]
	v_cvt_pk_f16_f32 v52, v56, v57
	v_pk_fma_f32 v[56:57], v[56:57], v[56:57], v[54:55]
	v_cvt_pk_f16_f32 v53, v58, v59
	v_pk_add_f32 v[58:59], v[62:63], v[64:65]
	v_pk_fma_f32 v[56:57], v[62:63], v[62:63], v[56:57]
	v_add_u32_e32 v2, v138, v97
	v_cvt_pk_f16_f32 v54, v62, v63
	v_cvt_pk_f16_f32 v55, v60, v61
	v_pk_add_f32 v[58:59], v[60:61], v[58:59]
	v_pk_fma_f32 v[56:57], v[60:61], v[60:61], v[56:57]
	v_lshl_add_u64 v[60:61], v[2:3], 1, s[10:11]
	global_store_dwordx4 v[60:61], v[52:55], off
	v_pk_add_f32 v[56:57], v[56:57], v[56:57] op_sel:[0,1] op_sel_hi:[1,0]
	s_nop 0
	v_pk_add_f32 v[52:53], v[58:59], v[58:59] op_sel:[0,1] op_sel_hi:[1,0]
	s_nop 0
	v_mov_b32_e32 v2, v52
	s_nop 1
	v_permlane16_swap_b32_e32 v52, v2
	v_add_f32_e32 v52, v52, v2
	v_mov_b32_e32 v2, v56
	s_nop 1
	v_permlane16_swap_b32_e32 v56, v2
	v_add_f32_e32 v53, v56, v2
	v_mov_b32_e32 v54, v52
	v_mov_b32_e32 v55, v53
	s_nop 0
	v_permlane32_swap_b32_e32 v52, v54
	v_permlane32_swap_b32_e32 v53, v55
	s_and_saveexec_b64 s[24:25], vcc
	s_cbranch_execz .LBB0_1786
	s_lshl_b32 s0, s56, 4
	v_mov_b32_e32 v125, v3
	s_ashr_i32 s1, s0, 31
	v_pk_add_f32 v[52:53], v[52:53], v[54:55]
	v_lshl_add_u64 v[54:55], v[124:125], 2, s[12:13]
	s_or_b64 s[0:1], s[0:1], s[64:65]
	v_lshl_add_u64 v[54:55], s[0:1], 2, v[54:55]
	global_store_dwordx2 v[54:55], v[52:53], off offset:32

.LBB0_1790:
	s_or_b64 exec, exec, s[24:25]
	s_waitcnt vmcnt(4)
	ds_read_b64 v[36:37], v175 offset:1024
	v_lshlrev_b32_e32 v38, 16, v84
	v_and_b32_e32 v39, 0xffff0000, v84
	v_lshlrev_b32_e32 v40, 16, v85
	v_and_b32_e32 v41, 0xffff0000, v85
	s_waitcnt lgkmcnt(0)
	v_mul_f32_e64 v2, v37, -v36
	v_pk_fma_f32 v[38:39], v[36:37], v[38:39], v[2:3] op_sel:[1,0,0] op_sel_hi:[1,1,0]
	v_lshlrev_b32_e32 v42, 16, v86
	v_and_b32_e32 v43, 0xffff0000, v86
	v_lshlrev_b32_e32 v44, 16, v87
	v_and_b32_e32 v45, 0xffff0000, v87
	v_pk_fma_f32 v[40:41], v[36:37], v[40:41], v[2:3] op_sel:[1,0,0] op_sel_hi:[1,1,0]
	v_pk_fma_f32 v[42:43], v[36:37], v[42:43], v[2:3] op_sel:[1,0,0] op_sel_hi:[1,1,0]
	v_pk_fma_f32 v[36:37], v[36:37], v[44:45], v[2:3] op_sel:[1,0,0] op_sel_hi:[1,1,0]
	v_pk_fma_f32 v[38:39], v[112:113], v[38:39], v[98:99]
	v_pk_fma_f32 v[40:41], v[114:115], v[40:41], v[106:107]
	v_pk_fma_f32 v[36:37], v[122:123], v[36:37], v[110:111]
	v_pk_fma_f32 v[32:33], v[32:33], 0.5, v[38:39] op_sel_hi:[1,0,1]
	v_pk_fma_f32 v[34:35], v[34:35], 0.5, v[40:41] op_sel_hi:[1,0,1]
	v_pk_fma_f32 v[36:37], v[30:31], 0.5, v[36:37] op_sel_hi:[1,0,1]
	v_pk_add_f32 v[30:31], v[32:33], 0 op_sel_hi:[1,0]
	v_pk_fma_f32 v[42:43], v[120:121], v[42:43], v[108:109]
	v_pk_add_f32 v[40:41], v[34:35], v[30:31]
	v_pk_mul_f32 v[30:31], v[34:35], v[34:35]
	v_pk_fma_f32 v[38:39], v[28:29], 0.5, v[42:43] op_sel_hi:[1,0,1]
	v_cvt_pk_f16_f32 v28, v32, v33
	v_pk_fma_f32 v[32:33], v[32:33], v[32:33], v[30:31]
	v_cvt_pk_f16_f32 v29, v34, v35
	v_pk_add_f32 v[34:35], v[38:39], v[40:41]
	v_pk_fma_f32 v[32:33], v[38:39], v[38:39], v[32:33]
	v_add_u32_e32 v2, v139, v97
	v_cvt_pk_f16_f32 v30, v38, v39
	v_cvt_pk_f16_f32 v31, v36, v37
	v_pk_add_f32 v[34:35], v[36:37], v[34:35]
	v_pk_fma_f32 v[32:33], v[36:37], v[36:37], v[32:33]
	v_lshl_add_u64 v[36:37], v[2:3], 1, s[10:11]
	global_store_dwordx4 v[36:37], v[28:31], off
	v_pk_add_f32 v[32:33], v[32:33], v[32:33] op_sel:[0,1] op_sel_hi:[1,0]
	s_nop 0
	v_pk_add_f32 v[28:29], v[34:35], v[34:35] op_sel:[0,1] op_sel_hi:[1,0]
	s_nop 0
	v_mov_b32_e32 v2, v28
	s_nop 1
	v_permlane16_swap_b32_e32 v28, v2
	v_add_f32_e32 v28, v28, v2
	v_mov_b32_e32 v2, v32
	s_nop 1
	v_permlane16_swap_b32_e32 v32, v2
	v_add_f32_e32 v29, v32, v2
	v_mov_b32_e32 v30, v28
	v_mov_b32_e32 v31, v29
	s_nop 0
	v_permlane32_swap_b32_e32 v28, v30
	v_permlane32_swap_b32_e32 v29, v31
	s_and_saveexec_b64 s[24:25], vcc
	s_cbranch_execz .LBB0_1792
	s_lshl_b32 s0, s56, 4
	v_mov_b32_e32 v105, v3
	s_ashr_i32 s1, s0, 31
	v_pk_add_f32 v[28:29], v[28:29], v[30:31]
	v_lshl_add_u64 v[30:31], v[104:105], 2, s[12:13]
	s_or_b64 s[0:1], s[0:1], s[64:65]
	v_lshl_add_u64 v[30:31], s[0:1], 2, v[30:31]
	global_store_dwordx2 v[30:31], v[28:29], off offset:32
